# short-conv phase: the rows of a trip's tasks 2-4 touched together with task 1's loads (each task's loads sat behind its own vmcnt(0))
# baseline (speedup 1.0000x reference)
.LBB0_102:
	v_and_b32_e32 v2, 0x3f8, v48
	v_ashrrev_i32_e32 v44, 7, v49
	v_lshlrev_b32_e32 v128, 1, v2
	v_ashrrev_i32_e32 v45, 31, v44
	v_lshl_add_u64 v[42:43], s[12:13], 0, v[128:129]
	v_lshlrev_b64 v[0:1], 12, v[44:45]
	v_lshl_add_u64 v[0:1], v[42:43], 0, v[0:1]
	flat_load_dwordx4 v[28:31], v[0:1]
	flat_load_dwordx4 v[24:27], v[0:1] offset:2048
	s_lshl_b32 vcc_lo, s14, 5
	s_mov_b32 vcc_hi, 0
	v_lshl_add_u64 v[130:131], v[0:1], 0, vcc
	flat_load_dwordx4 v[132:135], v[130:131]
	flat_load_dwordx4 v[136:139], v[130:131] offset:2048
	v_lshl_add_u64 v[130:131], v[130:131], 0, vcc
	flat_load_dwordx4 v[140:143], v[130:131]
	flat_load_dwordx4 v[144:147], v[130:131] offset:2048
	v_lshl_add_u64 v[130:131], v[130:131], 0, vcc
	flat_load_dwordx4 v[148:151], v[130:131]
	flat_load_dwordx4 v[152:155], v[130:131] offset:2048
	v_ashrrev_i32_e32 v3, 31, v49
	v_lshrrev_b32_e32 v3, 19, v3
	v_add_u32_e32 v3, v44, v3
	v_and_b32_e32 v3, 0xffffe000, v3
	v_sub_u32_e32 v3, v44, v3
	v_mov_b32_e32 v36, 0
	v_cmp_lt_i32_e32 vcc, 0, v3
	v_mov_b32_e32 v32, 0
	v_mov_b32_e32 v33, 0
	v_mov_b32_e32 v34, 0
	v_mov_b32_e32 v35, 0
	s_and_saveexec_b64 s[68:69], vcc
	s_cbranch_execz .LBB0_104
	v_add_co_u32_e32 v4, vcc, 0xfffff800, v0
	s_nop 1
	v_addc_co_u32_e32 v5, vcc, -1, v1, vcc
	flat_load_dwordx4 v[32:35], v[4:5]
